# role alternation phases +3/+5: 25% of the 8-unit blocks reordered
# baseline (speedup 1.0000x reference)
; #define SUB(k, bit) (!(kargs()->li == 1 && (k) == lo) || ((kargs()->submask >> (bit)) & 1u))
; __global__ void __launch_bounds__(NWAVES * 64, 2) fwd(Args args_unused) {
;     ...
;         if (IN(pb + 3)) {
;             PH_PTRS PH_LAYER
;             if (SUB(pb + 3, 0)) {
.LBB0_1364:
	v_readlane_b32 s99, v254, 3
	s_nop 3
	s_lshr_b32 s99, s99, 3
	s_and_b32 s99, s99, 3
	s_mov_b32 s98, 2
	s_cmp_eq_u32 s99, 3
	s_cselect_b32 s98, 0, s98
